# MAIN input-projection GEMM unit order through a lookup table: each workgroup's four units now mix gelu/silu/rope/raw epilogues (gelu,silu,rope,raw or rope,silu,silu-or-raw,raw) instead of gelu,silu,ra
# speedup vs baseline: 1.0069x; 1.0069x over previous
; __device__ __forceinline__ unsigned xb_ld(unsigned* p)              { return __hip_atomic_load(p, __ATOMIC_RELAXED, __HIP_MEMORY_SCOPE_AGENT); }
; __device__ __forceinline__ unsigned pk2(float lo, float hi) { return f2bf(lo) | (f2bf(hi) << 16); }
; #define RETID() do { tid = tidx(); lane = tid & 63; wave = tid >> 6; gw = bid * 8 + wave; } while (0)
; __global__ void __launch_bounds__(512, 2) mega(Params p) {
;     ...
;     bool fusedN = (G == 256);
;     { unsigned* bar_ = (unsigned*)(ws + WS_CTL); int nxc = 0;
;       for (int q_ = 0; q_ < 16; ++q_) { const unsigned c_ = xb_ld(&bar_[XB_XCNT(q_)]); if (c_) { ++nxc; if (c_ != 32u || q_ >= 8) fusedN = false; } }
;       if (nxc != 8) fusedN = false; }
;     if (PROBE_DUP == 8) { for (int q_ = 0; q_ < 20; ++q_) GSYNC(); }
;     for (int l = 0; l < 4; ++l) {
;         const float* mod = MOD + (size_t)l * 2 * 6144;
; if (!fusedN || l == 0)
; for (int rep_ = 0; rep_ < (PROBE_DUP == 1 ? 2 : 1); ++rep_) {
;         RETID();
;         { const float* nw = p.in[6] + (size_t)l * DM;
;           for (int row = gw; row < TT; row += ngw) {
;               const float4* xr = (const float4*)(l == 0 ? (row < TL ? p.in[0] + (size_t)row * DM : p.in[2] + (size_t)(row - TL) * DM) : X + (size_t)row * DM) + lane; float4 v[8]; float ss = 0.f;
; #pragma unroll
;               for (int j = 0; j < 8; ++j) { v[j] = xr[64 * j]; ss += v[j].x * v[j].x + v[j].y * v[j].y + v[j].z * v[j].z + v[j].w * v[j].w; }
;               const float r = rsqrtf(wave_sum(ss) * (1.f / DM) + EPS);
;               const float* md = mod + (row >= TL ? 6144 : 0);
;               uint2* hp = (uint2*)(H + (size_t)row * DM) + lane;
; #pragma unroll
;               for (int j = 0; j < 8; ++j) { const int col = 4 * (lane + 64 * j); const float4 w4 = *(const float4*)(nw + col), sc = *(const float4*)(md + 2048 + col), sh = *(const float4*)(md + col);
;                   uint2 o; o.x = pk2(v[j].x * r * w4.x * (1.f + sc.x) + sh.x, v[j].y * r * w4.y * (1.f + sc.y) + sh.y);
;                   o.y = pk2(v[j].z * r * w4.z * (1.f + sc.z) + sh.z, v[j].w * r * w4.w * (1.f + sc.w) + sh.w); hp[64 * j] = o; } } }
;         GSYNC();
; }
;         { pg8::Gemm g{H, WIN + (size_t)l * 8192 * 2048, TT, DIN, DM}; pg8::MainOrder S; S.init(TL, DIN, G, bid);
;           pg8::EpiProj E{P};
;           pg8::gemm_phase<pg8::EpiProj, pg8::MainOrder, true, true>(L, g, S, E); }
.LBB0_41:
	s_or_b64 exec, exec, s[0:1]
	v_mov_b32_e32 v0, 0x22dc0000
	s_barrier
	global_load_dword v1, v0, s[58:59] offset:1280 sc1
	global_load_dword v2, v0, s[58:59] offset:1536 sc1
	global_load_dword v3, v0, s[58:59] offset:1792 sc1
	global_load_dword v4, v0, s[58:59] offset:2048 sc1
	global_load_dword v5, v0, s[58:59] offset:2304 sc1
	global_load_dword v6, v0, s[58:59] offset:2560 sc1
	global_load_dword v7, v0, s[58:59] offset:2816 sc1
	v_mov_b32_e32 v8, 0x22dc1000
	global_load_dword v9, v0, s[58:59] offset:3072 sc1
	global_load_dword v10, v0, s[58:59] offset:3328 sc1
	global_load_dword v11, v0, s[58:59] offset:3584 sc1
	global_load_dword v12, v0, s[58:59] offset:3840 sc1
	global_load_dword v13, v8, s[58:59] sc1
	global_load_dword v14, v8, s[58:59] offset:256 sc1
	global_load_dword v15, v8, s[58:59] offset:512 sc1
	global_load_dword v16, v8, s[58:59] offset:768 sc1
	global_load_dword v17, v8, s[58:59] offset:1024 sc1
	s_add_u32 s88, s58, 0xa000000
	s_addc_u32 s89, s59, 0
	s_add_u32 s40, s58, 0xe200000
	s_addc_u32 s41, s59, 0
	s_add_u32 s78, s58, 0x10300000
	s_addc_u32 s79, s59, 0
	s_add_u32 s24, s58, 0x18808000
	s_addc_u32 s25, s59, 0
	s_add_u32 s0, s58, 0x1a908000
	s_addc_u32 s1, s59, 0
	s_add_u32 s28, s58, 0x1eb08000
	v_writelane_b32 v251, s0, 42
	s_addc_u32 s29, s59, 0
	s_mov_b64 s[94:95], s[58:59]
	v_writelane_b32 v251, s1, 43
	s_add_u32 s0, s58, 0x22d08000
	s_addc_u32 s1, s59, 0
	s_cmpk_eq_i32 s96, 0x100
	s_cselect_b64 s[34:35], -1, 0
	s_mov_b64 s[92:93], s[56:57]
	s_add_u32 s56, s94, 0x22dc0500
	s_addc_u32 s57, s95, 0
	v_writelane_b32 v251, s0, 44
	v_cndmask_b32_e64 v0, 0, 1, s[34:35]
	s_mov_b32 s85, 0
	v_writelane_b32 v251, s1, 45
	s_mov_b64 s[90:91], s[54:55]
	s_mov_b64 s[52:53], s[92:93]
	s_mov_b64 s[54:55], s[94:95]
	s_mov_b32 s43, s85
	s_mul_i32 s97, s97, s96
	s_mul_i32 s97, s97, s23
	v_mov_b32_e32 v165, 0
	v_mov_b32_e32 v179, 0x358637bd
	v_mov_b32_e32 v180, 1
	v_mov_b32_e32 v183, 0x41b17218
	s_movk_i32 s93, 0x4080
	s_movk_i32 s82, 0x6000
	s_mov_b32 s71, 0xffff0000
	s_mov_b32 s73, 0x7f800000
	s_mov_b64 s[76:77], 0x80
	s_mov_b32 s92, 0x3f07dc22
	s_mov_b32 s72, 0x3f35f0e3
	s_mov_b32 s70, 0xbe11a98e
	s_waitcnt vmcnt(15)
	v_cmp_eq_u32_e32 vcc, 32, v1
	s_and_b64 s[30:31], vcc, s[34:35]
	s_waitcnt vmcnt(14)
	v_cmp_ne_u32_e64 s[4:5], 0, v2
	v_cndmask_b32_e64 v8, 0, 1, s[30:31]
	v_cmp_ne_u32_e32 vcc, 0, v1
	v_cmp_eq_u32_e64 s[0:1], 32, v2
	v_cndmask_b32_e64 v2, 0, 1, s[4:5]
	v_cndmask_b32_e32 v0, v0, v8, vcc
	v_addc_co_u32_e32 v1, vcc, 0, v2, vcc
	v_and_b32_e32 v2, 1, v0
	s_add_u32 s58, s94, 0x22dc0600
	v_cmp_eq_u32_e32 vcc, 1, v2
	s_addc_u32 s59, s95, 0
	s_and_b64 s[0:1], s[0:1], vcc
	v_cndmask_b32_e64 v2, 0, 1, s[0:1]
	v_cndmask_b32_e64 v0, v0, v2, s[4:5]
	v_and_b32_e32 v2, 1, v0
	s_waitcnt vmcnt(13)
	v_cmp_eq_u32_e64 s[6:7], 32, v3
	s_add_u32 s30, s94, 0x22dc0700
	v_cmp_eq_u32_e32 vcc, 1, v2
	s_addc_u32 s31, s95, 0
	s_and_b64 s[0:1], s[6:7], vcc
	v_cmp_ne_u32_e64 s[8:9], 0, v3
	v_cndmask_b32_e64 v2, 0, 1, s[0:1]
	s_waitcnt vmcnt(12)
	v_cmp_eq_u32_e64 s[10:11], 32, v4
	v_cndmask_b32_e64 v0, v0, v2, s[8:9]
	v_and_b32_e32 v2, 1, v0
	s_add_u32 s48, s94, 0x22dc0800
	v_cmp_eq_u32_e32 vcc, 1, v2
	s_addc_u32 s49, s95, 0
	s_and_b64 s[0:1], s[10:11], vcc
	v_cndmask_b32_e64 v2, 0, 1, s[0:1]
	v_cmp_ne_u32_e32 vcc, 0, v4
	v_cndmask_b32_e64 v3, 0, 1, s[8:9]
	s_waitcnt vmcnt(11)
	v_cmp_eq_u32_e64 s[12:13], 32, v5
	v_cndmask_b32_e32 v0, v0, v2, vcc
	v_addc_co_u32_e32 v1, vcc, v1, v3, vcc
	v_and_b32_e32 v2, 1, v0
	s_add_u32 s74, s94, 0x22dc0900
	v_cmp_eq_u32_e32 vcc, 1, v2
	s_addc_u32 s75, s95, 0
	s_and_b64 s[0:1], s[12:13], vcc
	v_cmp_ne_u32_e64 s[14:15], 0, v5
	v_cndmask_b32_e64 v2, 0, 1, s[0:1]
	s_add_u32 s0, s94, 0x22dc0a00
	v_cndmask_b32_e64 v0, v0, v2, s[14:15]
	v_and_b32_e32 v2, 1, v0
	s_addc_u32 s1, s95, 0
	s_waitcnt vmcnt(10)
	v_cmp_eq_u32_e64 s[16:17], 32, v6
	v_writelane_b32 v251, s0, 46
	v_cmp_eq_u32_e32 vcc, 1, v2
	v_cndmask_b32_e64 v5, 0, 1, s[14:15]
	v_writelane_b32 v251, s1, 47
	s_and_b64 s[0:1], s[16:17], vcc
	v_cndmask_b32_e64 v2, 0, 1, s[0:1]
	v_cmp_ne_u32_e32 vcc, 0, v6
	s_add_u32 s0, s94, 0x22dc0b00
	s_addc_u32 s1, s95, 0
	v_cndmask_b32_e32 v0, v0, v2, vcc
	v_addc_co_u32_e32 v1, vcc, v1, v5, vcc
	v_and_b32_e32 v2, 1, v0
	s_waitcnt vmcnt(9)
	v_cmp_eq_u32_e64 s[18:19], 32, v7
	v_writelane_b32 v251, s0, 48
	v_cmp_eq_u32_e32 vcc, 1, v2
	v_cmp_ne_u32_e64 s[20:21], 0, v7
	v_writelane_b32 v251, s1, 49
	s_and_b64 s[0:1], s[18:19], vcc
	v_cndmask_b32_e64 v2, 0, 1, s[0:1]
	s_add_u32 s0, s94, 0x22dc0c00
	v_cndmask_b32_e64 v0, v0, v2, s[20:21]
	s_addc_u32 s1, s95, 0
	v_and_b32_e32 v2, 1, v0
	v_writelane_b32 v251, s0, 50
	v_cmp_eq_u32_e32 vcc, 1, v2
	v_cndmask_b32_e64 v7, 0, 1, s[20:21]
	v_writelane_b32 v251, s1, 51
	s_waitcnt vmcnt(8)
	v_cmp_eq_u32_e64 s[0:1], 32, v9
	s_and_b64 s[0:1], s[0:1], vcc
	v_cmp_ne_u32_e32 vcc, 0, v9
	v_cndmask_b32_e64 v2, 0, 1, s[0:1]
	s_add_u32 s0, s94, 0x22dc0d00
	s_addc_u32 s1, s95, 0
	v_cndmask_b32_e32 v0, v0, v2, vcc
	v_writelane_b32 v251, s0, 52
	v_addc_co_u32_e32 v1, vcc, v1, v7, vcc
	v_and_b32_e32 v0, 1, v0
	v_writelane_b32 v251, s1, 53
	s_waitcnt vmcnt(7)
	v_cmp_ne_u32_e64 s[0:1], 0, v10
	v_cmp_eq_u32_e32 vcc, 1, v0
	s_waitcnt vmcnt(0)
; __device__ __forceinline__ unsigned xb_ld(unsigned* p)              { return __hip_atomic_load(p, __ATOMIC_RELAXED, __HIP_MEMORY_SCOPE_AGENT); }
; __device__ __forceinline__ unsigned pk2(float lo, float hi) { return f2bf(lo) | (f2bf(hi) << 16); }
; #define RETID() do { tid = tidx(); lane = tid & 63; wave = tid >> 6; gw = bid * 8 + wave; } while (0)
; __global__ void __launch_bounds__(512, 2) mega(Params p) {
;     ...
;     bool fusedN = (G == 256);
;     { unsigned* bar_ = (unsigned*)(ws + WS_CTL); int nxc = 0;
;       for (int q_ = 0; q_ < 16; ++q_) { const unsigned c_ = xb_ld(&bar_[XB_XCNT(q_)]); if (c_) { ++nxc; if (c_ != 32u || q_ >= 8) fusedN = false; } }
;       if (nxc != 8) fusedN = false; }
;     if (PROBE_DUP == 8) { for (int q_ = 0; q_ < 20; ++q_) GSYNC(); }
;     for (int l = 0; l < 4; ++l) {
;         const float* mod = MOD + (size_t)l * 2 * 6144;
; if (!fusedN || l == 0)
; for (int rep_ = 0; rep_ < (PROBE_DUP == 1 ? 2 : 1); ++rep_) {
;         RETID();
;         { const float* nw = p.in[6] + (size_t)l * DM;
;           for (int row = gw; row < TT; row += ngw) {
;               const float4* xr = (const float4*)(l == 0 ? (row < TL ? p.in[0] + (size_t)row * DM : p.in[2] + (size_t)(row - TL) * DM) : X + (size_t)row * DM) + lane; float4 v[8]; float ss = 0.f;
; #pragma unroll
;               for (int j = 0; j < 8; ++j) { v[j] = xr[64 * j]; ss += v[j].x * v[j].x + v[j].y * v[j].y + v[j].z * v[j].z + v[j].w * v[j].w; }
;               const float r = rsqrtf(wave_sum(ss) * (1.f / DM) + EPS);
;               const float* md = mod + (row >= TL ? 6144 : 0);
;               uint2* hp = (uint2*)(H + (size_t)row * DM) + lane;
; #pragma unroll
;               for (int j = 0; j < 8; ++j) { const int col = 4 * (lane + 64 * j); const float4 w4 = *(const float4*)(nw + col), sc = *(const float4*)(md + 2048 + col), sh = *(const float4*)(md + col);
;                   uint2 o; o.x = pk2(v[j].x * r * w4.x * (1.f + sc.x) + sh.x, v[j].y * r * w4.y * (1.f + sc.y) + sh.y);
;                   o.y = pk2(v[j].z * r * w4.z * (1.f + sc.z) + sh.z, v[j].w * r * w4.w * (1.f + sc.w) + sh.w); hp[64 * j] = o; } } }
;         GSYNC();
; }
;         { pg8::Gemm g{H, WIN + (size_t)l * 8192 * 2048, TT, DIN, DM}; pg8::MainOrder S; S.init(TL, DIN, G, bid);
;           pg8::EpiProj E{P};
;           pg8::gemm_phase<pg8::EpiProj, pg8::MainOrder, true, true>(L, g, S, E); }
	v_or_b32_e32 v2, v17, v16
	v_cndmask_b32_e64 v0, 0, 1, s[0:1]
	s_add_u32 s0, s94, 0x22dc0e00
	s_addc_u32 s1, s95, 0
	v_writelane_b32 v251, s0, 54
	s_nop 1
	v_writelane_b32 v251, s1, 55
	v_cmp_ne_u32_e64 s[0:1], 0, v11
	s_nop 1
	v_addc_co_u32_e64 v0, s[0:1], v1, v0, s[0:1]
	s_add_u32 s0, s94, 0x22dc0f00
	s_addc_u32 s1, s95, 0
	v_writelane_b32 v251, s0, 56
	s_nop 1
	v_writelane_b32 v251, s1, 57
	v_cmp_ne_u32_e64 s[0:1], 0, v12
	s_nop 1
	v_cndmask_b32_e64 v1, 0, 1, s[0:1]
	s_add_u32 s0, s94, 0x22dc1000
	s_addc_u32 s1, s95, 0
	v_writelane_b32 v251, s0, 58
	s_add_u32 s36, s94, 0x22dc1100
	s_addc_u32 s37, s95, 0
	v_writelane_b32 v251, s1, 59
	v_cmp_ne_u32_e64 s[0:1], 0, v13
	s_add_u32 s68, s94, 0x22dc1200
	s_addc_u32 s69, s95, 0
	v_addc_co_u32_e64 v0, s[0:1], v0, v1, s[0:1]
	v_cmp_ne_u32_e64 s[0:1], 0, v14
	s_add_u32 s86, s94, 0x22dc1300
	s_addc_u32 s87, s95, 0
	v_cndmask_b32_e64 v1, 0, 1, s[0:1]
	v_cmp_ne_u32_e64 s[0:1], 0, v15
	s_add_u32 s80, s94, 0x22dc1400
	s_addc_u32 s81, s95, 0
	v_addc_co_u32_e64 v0, s[0:1], v0, v1, s[0:1]
	v_cmp_ne_u32_e64 s[0:1], 0, v16
	s_nop 1
	v_cndmask_b32_e64 v1, 0, 1, s[0:1]
	v_cmp_ne_u32_e64 s[0:1], 0, v17
	s_nop 1
	v_addc_co_u32_e64 v0, s[0:1], v0, v1, s[0:1]
	v_or_b32_e32 v1, v2, v15
	v_or_b32_e32 v1, v1, v14
	v_or_b32_e32 v1, v1, v13
	v_or_b32_e32 v1, v1, v12
	v_or_b32_e32 v1, v1, v11
	v_or_b32_e32 v1, v1, v10
	v_cmp_eq_u32_e64 s[0:1], 0, v1
	v_cmp_eq_u32_e64 s[4:5], 8, v0
	s_and_b64 s[0:1], s[4:5], s[0:1]
	s_and_b64 s[0:1], s[0:1], vcc
	v_writelane_b32 v251, s0, 60
	v_sub_co_u32_e64 v0, s[38:39], s2, 20
	s_nop 0
	v_writelane_b32 v251, s1, 61
	s_xor_b64 s[0:1], s[0:1], -1
	v_writelane_b32 v251, s0, 62
	s_nop 1
	v_writelane_b32 v251, s1, 63
	s_add_u32 s0, s94, 0x22dc0300
	s_addc_u32 s1, s95, 0
	v_writelane_b32 v252, s0, 0
	s_cmp_eq_u32 s22, 15
	v_readlane_b32 s12, v251, 38
	v_writelane_b32 v252, s1, 1
	s_cselect_b64 s[0:1], -1, 0
	v_writelane_b32 v252, s0, 2
	s_cmp_eq_u32 s22, 14
	v_readlane_b32 s13, v251, 39
	v_writelane_b32 v252, s1, 3
	s_cselect_b64 s[0:1], -1, 0
	v_writelane_b32 v252, s0, 4
	s_cmp_eq_u32 s22, 13
	s_nop 0
	v_writelane_b32 v252, s1, 5
	s_cselect_b64 s[0:1], -1, 0
	v_writelane_b32 v252, s0, 6
	s_cmp_eq_u32 s22, 12
	s_nop 0
	v_writelane_b32 v252, s1, 7
	s_cselect_b64 s[0:1], -1, 0
	v_writelane_b32 v252, s0, 8
	s_cmp_eq_u32 s22, 11
	s_nop 0
	v_writelane_b32 v252, s1, 9
	s_cselect_b64 s[0:1], -1, 0
	v_writelane_b32 v252, s0, 10
	s_cmp_eq_u32 s22, 10
	s_nop 0
	v_writelane_b32 v252, s1, 11
	s_cselect_b64 s[0:1], -1, 0
	v_writelane_b32 v252, s0, 12
	s_cmp_eq_u32 s22, 9
	s_nop 0
	v_writelane_b32 v252, s1, 13
	s_cselect_b64 s[0:1], -1, 0
	v_writelane_b32 v252, s0, 14
	s_cmp_eq_u32 s22, 8
	s_nop 0
	v_writelane_b32 v252, s1, 15
	s_cselect_b64 s[0:1], -1, 0
	v_writelane_b32 v252, s0, 16
	s_cmp_eq_u32 s22, 7
	s_nop 0
	v_writelane_b32 v252, s1, 17
	s_cselect_b64 s[0:1], -1, 0
	v_writelane_b32 v252, s0, 18
	s_cmp_eq_u32 s22, 6
	s_nop 0
	v_writelane_b32 v252, s1, 19
	s_cselect_b64 s[0:1], -1, 0
	v_writelane_b32 v252, s0, 20
	s_cmp_eq_u32 s22, 5
	s_nop 0
	v_writelane_b32 v252, s1, 21
	s_cselect_b64 s[0:1], -1, 0
	v_writelane_b32 v252, s0, 22
	s_cmp_eq_u32 s22, 4
	s_nop 0
	v_writelane_b32 v252, s1, 23
	s_cselect_b64 s[0:1], -1, 0
	v_writelane_b32 v252, s0, 24
	s_cmp_eq_u32 s22, 3
	s_nop 0
	v_writelane_b32 v252, s1, 25
	s_cselect_b64 s[0:1], -1, 0
	v_writelane_b32 v252, s0, 26
	s_cmp_eq_u32 s22, 2
	s_nop 0
	v_writelane_b32 v252, s1, 27
	s_cselect_b64 s[0:1], -1, 0
	v_writelane_b32 v252, s0, 28
	s_cmp_eq_u32 s22, 1
	s_nop 0
	v_writelane_b32 v252, s1, 29
	s_cselect_b64 s[0:1], -1, 0
	v_writelane_b32 v252, s0, 30
	s_cmp_eq_u32 s22, 0
	s_nop 0
	v_writelane_b32 v252, s1, 31
	s_cselect_b64 s[0:1], -1, 0
	v_writelane_b32 v252, s0, 32
	s_lshl_b32 s42, s22, 6
	s_nop 0
	v_writelane_b32 v252, s1, 33
	s_lshl_b32 s0, s22, 8
	s_add_u32 s0, s60, s0
	s_addc_u32 s1, s61, 0
	s_add_u32 s4, s0, 0x1400
	s_addc_u32 s5, s1, 0
	v_writelane_b32 v252, s4, 34
	s_add_u32 s0, s0, 0x2400
	s_addc_u32 s1, s1, 0
	v_writelane_b32 v252, s5, 35
	v_writelane_b32 v252, s0, 36
	s_mov_b64 s[60:61], s[30:31]
	s_nop 0
	v_writelane_b32 v252, s1, 37
	s_add_u32 s0, s94, 0x22dc3500
	s_addc_u32 s1, s95, 0
	v_writelane_b32 v252, s0, 38
	s_nop 1
	v_writelane_b32 v252, s1, 39
	s_add_u32 s0, s94, 0x22dc3600
	s_addc_u32 s1, s95, 0
	v_writelane_b32 v252, s0, 40
	s_cmpk_lt_i32 s2, 0x400
	s_nop 0
	v_writelane_b32 v252, s1, 41
	s_cselect_b64 s[0:1], -1, 0
	v_writelane_b32 v252, s0, 42
	s_ashr_i32 s3, s2, 31
	s_nop 0
	v_writelane_b32 v252, s1, 43
	s_lshr_b32 s0, s3, 29
	s_add_i32 s0, s2, s0
	s_ashr_i32 s11, s0, 3
	s_and_b32 s0, s0, -8
	s_sub_i32 s16, s2, s0
	s_lshl_b32 s17, s16, 7
	s_ashr_i32 s0, s96, 31
	v_writelane_b32 v252, s0, 44
	s_add_u32 s0, s94, 0x22dc3800
	v_writelane_b32 v252, s0, 45
	s_addc_u32 s0, s95, 0
	s_cmp_gt_i32 s2, 31
	v_writelane_b32 v252, s0, 46
	s_cselect_b64 s[0:1], -1, 0
	v_writelane_b32 v252, s0, 47
	s_nop 1
	v_writelane_b32 v252, s1, 48
	s_sub_i32 s0, s2, 32
	v_writelane_b32 v252, s0, 49
	s_cmpk_lt_i32 s2, 0x338
	v_readfirstlane_b32 s0, v0
	s_cselect_b64 s[4:5], -1, 0
	s_lshr_b32 s0, s0, 2
	v_writelane_b32 v252, s4, 50
	s_sub_i32 s20, 31, s0
	s_and_b32 s0, s2, 3
	v_writelane_b32 v252, s5, 51
	s_or_b32 s21, s0, 28
	s_sub_i32 s0, s96, 32
	s_add_i32 s27, s2, 12
	s_add_i32 s30, s2, 6
	v_writelane_b32 v252, s0, 52
	s_add_u32 s0, s94, 0x22dc3700
	v_writelane_b32 v252, s0, 53
	s_addc_u32 s0, s95, 0
	v_writelane_b32 v252, s0, 54
	s_lshl_b32 s0, s2, 9
	s_lshl_b32 s65, s96, 9
	v_writelane_b32 v252, s0, 55
	s_cmp_gt_i32 s96, 31
	s_movk_i32 s0, 0x410
	s_cselect_b32 s0, s0, 0x420
	s_cmp_lt_i32 s2, s0
	v_writelane_b32 v252, s0, 56
	s_cselect_b64 s[0:1], -1, 0
;     __device__ bool next(int i, Unit& u) const { if (i != 0) return false; u.pm = pm; u.pn = pn; return true; }
; #define RETID() do { tid = tidx(); lane = tid & 63; wave = tid >> 6; gw = bid * 8 + wave; } while (0)
;     __device__ bool next(int i, Unit& u) const {
;         if (!StaticOrder::next(i, u)) return false;
;         if (u.pn >= 28 && u.pm >= 29) { const int j = (31 - u.pm) * 4 + (u.pn - 28); u.pm = 32; u.pn = (j < 6) ? j : 8 + (j - 6); }
;         return true;
; __global__ void __launch_bounds__(512, 2) mega(Params p) {
;     ...
;         { const float lam = LAM[l], li1 = 1.f - LAM[4 + l]; const float* sw = p.in[15] + (size_t)l * 256;
;           const int nrow = (l < 3) ? TT : TL;
;           const bool side = (l < 3) && (G >= 32);
;           const int apn = side ? (G - 16) * 8 : ngw;
;           if (side && bid >= G - 16) { RETID(); const int r = 512 + (bid - (G - 16)); hgrn_c_item(P, LB + (size_t)l * 512, LB + (size_t)(4 + l) * 512, ST, p.in[13] + (size_t)l * 128, Y, r >> 2, r & 3, L, tid); }
	v_writelane_b32 v252, s0, 57
	s_cmp_lt_i32 s96, 32
	v_mbcnt_lo_u32_b32 v0, -1, 0
	v_writelane_b32 v252, s1, 58
	s_cselect_b64 s[0:1], -1, 0
	v_writelane_b32 v252, s0, 59
	v_mbcnt_hi_u32_b32 v171, -1, v0
	v_and_b32_e32 v0, 64, v171
	v_writelane_b32 v252, s1, 60
	s_add_i32 s0, s62, 0xffffff80
	v_writelane_b32 v252, s0, 61
	s_add_i32 s0, s96, -16
	s_cmp_lt_i32 s2, s0
	s_cselect_b64 s[4:5], -1, 0
	s_sub_i32 s0, s2, s0
	v_writelane_b32 v252, s4, 62
	s_add_i32 s1, s0, 0x200
	v_add_u32_e32 v172, 64, v0
	v_writelane_b32 v252, s5, 63
	s_lshr_b32 s4, s1, 2
	s_and_b32 s5, s0, 3
	s_lshl_b32 s0, s4, 6
	s_lshl_b32 s6, s5, 7
	s_lshl_b32 s9, s5, 8
	v_writelane_b32 v253, s0, 0
	s_add_u32 s0, s78, s9
	s_addc_u32 s1, s79, 0
	v_writelane_b32 v253, s0, 1
	v_xor_b32_e32 v178, 1, v171
	v_xor_b32_e32 v177, 2, v171
	v_writelane_b32 v253, s1, 2
	s_lshl_b32 s0, s5, 9
	s_add_u32 s0, s12, s0
	v_writelane_b32 v253, s0, 3
	s_addc_u32 s0, s13, 0
	s_add_i32 s84, s4, 0xffffff80
	v_writelane_b32 v253, s0, 4
	s_lshl_b64 s[0:1], s[84:85], 18
	s_add_u32 s0, s28, s0
	s_addc_u32 s1, s29, s1
	s_lshl_b32 s5, s5, 16
	s_add_u32 s0, s0, s5
	v_writelane_b32 v253, s2, 5
	s_addc_u32 s1, s1, 0
	v_readlane_b32 s83, v253, 5
	v_writelane_b32 v253, s0, 6
	s_add_u32 s5, s28, s5
	s_addc_u32 s7, s29, 0
	v_writelane_b32 v253, s1, 7
	s_sub_i32 s0, 0x107, s4
	s_ashr_i32 s1, s0, 31
	s_lshl_b64 s[0:1], s[0:1], 18
	s_add_u32 s0, s5, s0
	s_addc_u32 s1, s7, s1
	v_writelane_b32 v253, s0, 8
	s_cmpk_lt_i32 s83, 0x100
	s_mov_b32 s84, s3
	v_writelane_b32 v253, s1, 9
	s_cselect_b64 s[0:1], -1, 0
	v_writelane_b32 v253, s0, 10
	v_readlane_b32 s2, v251, 34
	v_readlane_b32 s3, v251, 35
	v_writelane_b32 v253, s1, 11
	s_add_u32 s0, s94, 0xe000000
	v_writelane_b32 v253, s0, 12
	s_addc_u32 s0, s95, 0
	v_writelane_b32 v253, s0, 13
	s_add_u32 s0, s94, 0x22dc7c00
	v_writelane_b32 v253, s0, 14
	s_addc_u32 s0, s95, 0
	v_writelane_b32 v253, s0, 15
	s_lshl_b32 s0, s22, 2
	s_ashr_i32 s8, s26, 3
	s_add_i32 s12, s8, s0
	s_ashr_i32 s13, s12, 31
	s_and_b32 s19, s26, 7
	s_lshl_b32 s18, s16, 5
	s_lshl_b32 s10, s19, 20
	s_lshl_b64 s[0:1], s[12:13], 20
	s_add_u32 s2, s2, s10
	v_writelane_b32 v253, s2, 16
	s_addc_u32 s2, s3, 0
	s_add_u32 s14, s24, s0
	s_addc_u32 s15, s25, s1
	v_writelane_b32 v253, s2, 17
	s_add_u32 s2, s14, 0x80000
	s_addc_u32 s3, s15, 0
	v_writelane_b32 v253, s2, 18
	v_xor_b32_e32 v176, 4, v171
	s_movk_i32 s4, 0x20ff
	v_writelane_b32 v253, s3, 19
	s_lshl_b32 s2, s12, 8
	s_lshl_b32 s3, s19, 8
	s_cmp_gt_i32 s12, 31
	v_writelane_b32 v253, s3, 20
	s_cselect_b32 s7, 0x1800, 0
	s_add_u32 s3, s94, 0x22dcd000
	v_writelane_b32 v253, s3, 21
	s_addc_u32 s3, s95, 0
	v_writelane_b32 v253, s3, 22
	s_lshl_b32 s3, s12, 6
	s_lshl_b32 s12, s19, 5
	v_writelane_b32 v253, s3, 23
	s_or_b32 s13, s2, s12
	v_writelane_b32 v253, s2, 24
	s_or_b32 s2, s13, 24
	s_cmp_lt_i32 s26, 4
	v_writelane_b32 v253, s2, 25
	s_cselect_b64 s[2:3], -1, 0
	s_lshl_b32 s13, s26, 3
	s_lshl_b32 s19, s22, 5
	v_writelane_b32 v253, s2, 26
	s_add_i32 s13, s13, s19
	s_mul_i32 s19, s16, 0x81
	v_writelane_b32 v253, s3, 27
	s_add_i32 s2, s13, 0x2000
	s_cmp_lt_i32 s16, 0
	s_cselect_b32 s17, s19, s17
	s_mul_i32 s16, s16, 33
	s_cselect_b32 s26, s16, s18
	s_add_i32 s16, s17, s11
	s_ashr_i32 s17, s16, 31
	s_lshr_b32 s17, s17, 24
	s_add_i32 s17, s16, s17
	s_and_b32 s18, s17, 0xffffff00
	s_sub_i32 s16, s16, s18
	s_bfe_u32 s18, s16, 0x3001c
	s_add_i32 s18, s16, s18
	s_and_b32 s19, s18, 0xfff8
	s_ashr_i32 s17, s17, 8
	s_sub_i32 s19, s16, s19
	s_lshl_b32 s17, s17, 3
	s_sext_i32_i16 s19, s19
	s_add_i32 s31, s17, s19
	s_sext_i32_i16 s17, s18
	s_ashr_i32 s33, s17, 3
	s_lshr_b32 s18, s33, 4
	s_lshl_b32 s18, s18, 2
	s_add_i32 s33, s33, s18
	s_cmp_gt_i32 s33, 27
	s_cselect_b64 s[16:17], -1, 0
	s_cmp_gt_i32 s31, 28
	s_cselect_b64 s[18:19], -1, 0
	s_and_b64 s[16:17], s[16:17], s[18:19]
	s_lshl_b32 s18, s31, 2
	s_sub_i32 s18, s33, s18
	v_writelane_b32 v253, s2, 28
	s_cmpk_lt_i32 s18, 0xffa6
	s_movk_i32 s2, 0x60
	s_cselect_b32 s19, s2, 0x62
	s_add_i32 s19, s19, s18
	s_and_b64 s[16:17], s[16:17], exec
	s_cselect_b32 s46, s19, s33
	s_cselect_b32 s50, 32, s31
	s_and_b64 s[2:3], s[38:39], exec
	s_cselect_b32 s2, s27, s21
	s_cmp_lt_i32 s83, 2
	s_cselect_b32 s2, s30, s2
	s_cmp_lt_i32 s83, 20
	s_cselect_b32 s16, 32, s20
	s_cselect_b32 s17, 0, 3
	s_ashr_i32 s3, s2, 31
	s_lshl_b32 s18, s16, 20
	s_lshl_b64 s[20:21], s[2:3], 20
	s_add_u32 s30, s40, s18
	s_addc_u32 s31, s41, 0
	s_add_u32 s38, s30, 0x80000
	s_addc_u32 s39, s31, 0
	v_writelane_b32 v253, s38, 29
	s_lshl_b32 s3, s2, 8
	s_lshl_b32 s2, s2, 1
	v_writelane_b32 v253, s39, 30
	s_mov_b32 s38, 0x20002211
	s_and_b32 s2, s2, -4
	s_mov_b32 s39, 0x22003333
	v_writelane_b32 v253, s3, 31
	s_lshr_b64 s[2:3], s[38:39], s2
	s_and_b32 s2, s2, 3
	s_lshl_b32 s3, s16, 8
	s_cmp_eq_u32 s2, 3
	s_cselect_b32 s2, s17, s2
	v_writelane_b32 v253, s3, 32
	s_cmp_eq_u32 s2, 3
	v_writelane_b32 v253, s2, 33
	s_cselect_b64 s[2:3], -1, 0
	v_writelane_b32 v253, s2, 34
	s_movk_i32 s33, 0x90
	s_mov_b32 s27, 0x3f317217
	v_writelane_b32 v253, s3, 35
;     __device__ bool next(int i, Unit& u) const { if (i != 0) return false; u.pm = pm; u.pn = pn; return true; }
;     __host__ __device__ bool next(int i, Unit& u) const {
;         const long L = (long)i * G + c; if (L >= nwg) return false;
;         int wgid = (int)L; { const int q = nwg / NXCD, r = nwg % NXCD, xcd = wgid % NXCD, off = wgid / NXCD; wgid = (xcd < r ? xcd * (q + 1) : r * (q + 1) + (xcd - r) * q) + off; }
;         const int nig = WGM * nN, gid = wgid / nig, fm = gid * WGM, gsz = (nM - fm) < WGM ? (nM - fm) : WGM;
;         u.pm = fm + ((wgid % nig) % gsz); u.pn = (wgid % nig) / gsz; return true;
; __global__ void __launch_bounds__(512, 2) mega(Params p) {
;     ...
;         else
;         { const int M2 = TL;
;           pg8::Gemm g{Y, WOUT + (size_t)l * 2048 * 2048, M2, DM, DM}; pg8::StaticOrder S; S.init(M2, DM, G, bid);
;           pg8::EpiOut E{X, l == 0 ? p.in[0] : X, mod};
;           pg8::gemm_phase<pg8::EpiOut, pg8::StaticOrder, true, true>(L, g, S, E); }
	s_add_i32 s2, s26, s11
	s_ashr_i32 s3, s2, 31
	s_lshr_b32 s3, s3, 26
	s_add_i32 s3, s2, s3
	s_and_b32 s11, s3, 0xffc0
	s_sub_i32 s2, s2, s11
	s_bfe_i32 s11, s2, 0x80000
	s_bfe_u32 s11, s11, 0x3000c
	s_add_i32 s11, s2, s11
	s_and_b32 s16, s11, 0xf8
	s_sub_i32 s2, s2, s16
	s_ashr_i32 s3, s3, 6
	s_bfe_i32 s11, s11, 0x80000
	s_lshl_b32 s3, s3, 3
	s_sext_i32_i16 s11, s11
	s_sext_i32_i8 s2, s2
	s_add_i32 s16, s3, s2
	s_ashr_i32 s2, s11, 3
	v_writelane_b32 v253, s2, 36
	s_lshr_b32 s2, s11, 3
	s_bfe_i64 s[2:3], s[2:3], 0x100000
	s_lshl_b64 s[2:3], s[2:3], 20
	v_writelane_b32 v253, s2, 37
	s_ashr_i32 s17, s16, 31
	s_mov_b32 s26, 0x3e027906
	v_writelane_b32 v253, s3, 38
	s_mov_b32 s2, s16
	v_writelane_b32 v253, s2, 39
	s_nop 1
	v_writelane_b32 v253, s3, 40
	s_lshl_b64 s[2:3], s[16:17], 20
	s_add_u32 s2, s24, s2
	s_addc_u32 s3, s25, s3
	s_add_u32 s16, s2, 0x80000
	v_writelane_b32 v253, s2, 41
	s_addc_u32 s17, s3, 0
	s_ashr_i32 s47, s46, 31
	v_writelane_b32 v253, s3, 42
	v_writelane_b32 v253, s16, 43
	s_mov_b32 s2, s50
	s_ashr_i32 s51, s50, 31
	v_writelane_b32 v253, s17, 44
	v_writelane_b32 v253, s2, 45
	s_mov_b32 s16, s46
	s_nop 0
	v_writelane_b32 v253, s3, 46
	v_writelane_b32 v253, s16, 47
	s_lshl_b64 s[2:3], s[50:51], 20
	s_mov_b64 s[50:51], s[90:91]
	v_writelane_b32 v253, s17, 48
	s_lshl_b64 s[16:17], s[46:47], 20
	v_writelane_b32 v253, s16, 49
	s_add_u32 s2, s40, s2
	s_movk_i32 s47, 0x1000
	v_writelane_b32 v253, s17, 50
	v_writelane_b32 v253, s40, 51
	s_addc_u32 s3, s41, s3
	s_add_u32 s16, s2, 0x80000
	v_writelane_b32 v253, s41, 52
	v_writelane_b32 v253, s2, 53
	s_addc_u32 s17, s3, 0
	s_mov_b32 s91, 0x800000
	v_writelane_b32 v253, s3, 54
	v_writelane_b32 v253, s16, 55
	s_add_u32 s2, s24, s9
	s_addc_u32 s3, s25, 0
	v_writelane_b32 v253, s17, 56
	v_writelane_b32 v253, s2, 57
	s_ashr_i32 s67, s66, 31
	s_ashr_i32 s63, s62, 31
	v_writelane_b32 v253, s3, 58
	v_writelane_b32 v253, s66, 59
	s_lshl_b64 s[2:3], s[62:63], 13
	s_mov_b32 s90, 0x3e6d3388
	v_writelane_b32 v253, s67, 60
	v_writelane_b32 v253, s2, 61
	s_movk_i32 s67, 0x3000
	s_mov_b32 s66, 0x20000
	v_writelane_b32 v253, s3, 62
	s_add_u32 s2, s94, s18
	s_addc_u32 s3, s95, 0
	v_writelane_b32 v253, s2, 63
	s_add_u32 s2, s2, 0xe280080
	v_writelane_b32 v254, s3, 0
	s_addc_u32 s3, s3, 0
	v_writelane_b32 v254, s2, 1
	s_nop 1
	v_writelane_b32 v254, s3, 2
	s_add_u32 s2, s94, s20
	v_writelane_b32 v254, s20, 3
	s_addc_u32 s3, s95, s21
	s_add_u32 s2, s2, 0x100
	v_writelane_b32 v254, s21, 4
	v_writelane_b32 v254, s2, 5
	s_addc_u32 s2, s3, 0
	v_writelane_b32 v254, s2, 6
	s_add_u32 s2, s94, 0x10302810
	s_addc_u32 s3, s95, 0
	v_writelane_b32 v254, s2, 7
	s_nop 1
	v_writelane_b32 v254, s3, 8
	s_lshl_b32 s2, s83, 11
	v_writelane_b32 v254, s2, 9
	s_lshl_b32 s2, s83, 5
	v_writelane_b32 v254, s2, 10
	s_lshl_b32 s2, s96, 5
	s_add_u32 s0, s94, s0
	v_writelane_b32 v254, s2, 11
	s_addc_u32 s1, s95, s1
	v_writelane_b32 v254, s0, 12
	s_add_u32 s0, s0, 0x18888080
	v_writelane_b32 v254, s1, 13
	s_addc_u32 s1, s1, 0
	v_writelane_b32 v254, s0, 14
	s_mul_hi_i32 s3, s62, 0x4080
	s_mul_i32 s2, s62, 0x4080
	v_writelane_b32 v254, s1, 15
	v_writelane_b32 v254, s48, 16
	s_add_u32 s0, s94, s10
	s_addc_u32 s1, s95, 0
	v_writelane_b32 v254, s49, 17
	v_writelane_b32 v254, s50, 18
	v_writelane_b32 v254, s51, 19
	v_writelane_b32 v254, s52, 20
	v_writelane_b32 v254, s53, 21
	v_writelane_b32 v254, s54, 22
	v_writelane_b32 v254, s55, 23
	v_writelane_b32 v254, s42, 24
	s_add_u32 s16, s0, 0x8000100
	s_addc_u32 s17, s1, 0
	v_writelane_b32 v254, s43, 25
	s_lshl_b32 s0, s22, 10
	s_lshl_b32 s1, s8, 8
	v_writelane_b32 v254, s2, 26
	s_add_i32 s0, s0, s1
	s_add_i32 s1, s13, 0x1ff8
	v_writelane_b32 v254, s3, 27
	v_writelane_b32 v254, s1, 28
	s_xor_b64 s[2:3], s[34:35], -1
	v_writelane_b32 v254, s2, 29
	s_lshl_b32 s1, s7, 2
	s_or_b32 s0, s0, s12
	v_writelane_b32 v254, s3, 30
	v_writelane_b32 v254, s1, 31
	v_writelane_b32 v254, s0, 32
	s_add_i32 s0, s0, -8
	v_writelane_b32 v254, s0, 33
	s_add_i32 s0, 0, 0x23ff4
	v_writelane_b32 v254, s0, 34
	s_add_i32 s0, 0, 0x13200
	v_writelane_b32 v254, s0, 35
	s_add_i32 s0, 0, 0x19e00
	v_writelane_b32 v254, s0, 36
	s_add_i32 s0, 0, 0x22600
	v_writelane_b32 v254, s0, 37
	s_lshl_b32 s0, s6, 1
	v_writelane_b32 v254, s0, 38
	s_add_i32 s5, 0, 0x23ff0
	s_movk_i32 s95, 0x2000
	v_writelane_b32 v254, s1, 39
	v_writelane_b32 v254, s62, 40
	s_movk_i32 s3, 0x7fff
	s_movk_i32 s8, 0x110
	v_writelane_b32 v254, s63, 41
	v_writelane_b32 v254, s56, 42
	s_add_i32 s9, 0, 0x17a00
	s_movk_i32 s10, 0x1100
	v_writelane_b32 v254, s57, 43
	v_writelane_b32 v254, s58, 44
	s_mov_b32 s94, 0xbf3a00e3
	s_mov_b32 s2, 0xbf38aa3b
	v_writelane_b32 v254, s59, 45
	v_writelane_b32 v254, s60, 46
	s_mov_b32 s12, s85
	s_nop 0
	v_writelane_b32 v254, s61, 47
	v_writelane_b32 v254, s48, 48
	s_nop 1
	v_writelane_b32 v254, s49, 49
	v_writelane_b32 v254, s74, 50
	s_nop 1
	v_writelane_b32 v254, s75, 51
	v_writelane_b32 v254, s65, 52
	v_writelane_b32 v254, s5, 53
	v_writelane_b32 v254, s84, 54
	s_branch .LBB0_44

;     __device__ bool next(int i, Unit& u) const { if (i != 0) return false; u.pm = pm; u.pn = pn; return true; }
;     __host__ __device__ bool next(int i, Unit& u) const {
;     ...
;         int wgid = (int)L; { const int q = nwg / NXCD, r = nwg % NXCD, xcd = wgid % NXCD, off = wgid / NXCD; wgid = (xcd < r ? xcd * (q + 1) : r * (q + 1) + (xcd - r) * q) + off; }
;         const int nig = WGM * nN, gid = wgid / nig, fm = gid * WGM, gsz = (nM - fm) < WGM ? (nM - fm) : WGM;
;         u.pm = fm + ((wgid % nig) % gsz); u.pn = (wgid % nig) / gsz; return true;
;     __device__ bool next(int i, Unit& u) const {
;         if (!StaticOrder::next(i, u)) return false;
;         if (u.pn >= 28 && u.pm >= 29) { const int j = (31 - u.pm) * 4 + (u.pn - 28); u.pm = 32; u.pn = (j < 6) ? j : 8 + (j - 6); }
;         return true;
.LBB0_118:
	s_ashr_i32 s6, s13, 3
	s_add_i32 s6, s17, s6
	s_ashr_i32 s7, s6, 31
	s_lshr_b32 s7, s7, 24
	s_add_i32 s7, s6, s7
	s_ashr_i32 s13, s7, 8
	s_lshl_b32 s13, s13, 3
	s_sub_i32 s16, 32, s13
	s_min_i32 s16, s16, 8
	s_abs_i32 s17, s16
	v_cvt_f32_u32_e32 v0, s17
	s_sub_i32 s19, 0, s17
	s_and_b32 s7, s7, 0xffffff00
	s_sub_i32 s6, s6, s7
	v_rcp_iflag_f32_e32 v0, v0
	s_abs_i32 s7, s6
	s_xor_b32 s18, s6, s16
	s_ashr_i32 s18, s18, 31
	v_mul_f32_e32 v0, 0x4f7ffffe, v0
	v_cvt_u32_f32_e32 v0, v0
	s_nop 0
	v_readfirstlane_b32 s20, v0
	s_mul_i32 s19, s19, s20
	s_mul_hi_u32 s19, s20, s19
	s_add_i32 s20, s20, s19
	s_mul_hi_u32 s19, s7, s20
	s_mul_i32 s20, s19, s17
	s_sub_i32 s7, s7, s20
	s_add_i32 s21, s19, 1
	s_sub_i32 s20, s7, s17
	s_cmp_ge_u32 s7, s17
	s_cselect_b32 s19, s21, s19
	s_cselect_b32 s7, s20, s7
	s_add_i32 s20, s19, 1
	s_cmp_ge_u32 s7, s17
	s_cselect_b32 s7, s20, s19
	s_xor_b32 s7, s7, s18
	s_sub_i32 s18, s7, s18
	s_mul_i32 s7, s18, s16
	s_sub_i32 s6, s6, s7
	s_add_i32 s13, s13, s6
	s_lshr_b32 s6, s18, 2
	s_and_b32 s7, s18, 3
	s_cmp_eq_u32 s6, 6
	s_cselect_b32 s17, 2, 0
	s_xor_b32 s7, s7, s17
	s_lshl_b32 s6, s6, 3
	s_mov_b32 s16, 0x10080400
	s_mov_b32 s17, 0x180c1c14
	s_lshr_b64 s[16:17], s[16:17], s6
	s_and_b32 s16, s16, 0xff
	s_add_i32 s18, s16, s7
	s_cmp_gt_i32 s18, 27
	s_cselect_b64 s[6:7], -1, 0
	s_cmp_gt_i32 s13, 28
	s_cselect_b64 s[16:17], -1, 0
	s_and_b64 s[6:7], s[6:7], s[16:17]
	s_lshl_b32 s16, s13, 2
	s_sub_i32 s16, s18, s16
	s_cmpk_lt_i32 s16, 0xffa6
	s_movk_i32 s17, 0x60
	s_cselect_b32 s17, s17, 0x62
	s_add_i32 s17, s17, s16
	s_and_b64 s[6:7], s[6:7], exec
	s_cselect_b32 s46, s17, s18
	s_cselect_b32 s48, 32, s13
